# GEMM1a: rotate column-tile assignment per step so every WG gets the same mix of epilogue types
# baseline (speedup 1.0000x reference)
;     __device__ bool next(int i, Unit& u) const {
;     ...
;         const long L = (long)ti * G + c; if (L >= nwg) return false;
;         int wgid = (int)L; { const int q = nwg / NXCD, r = nwg % NXCD, xcd = wgid % NXCD, off = wgid / NXCD; wgid = (xcd < r ? xcd * (q + 1) : r * (q + 1) + (xcd - r) * q) + off; }
;         const int nig = wgm * nN, gid = wgid / nig, fm = gid * wgm, gsz = (nM - fm) < wgm ? (nM - fm) : wgm;
;         u.pm = fm + ((wgid % nig) % gsz); u.pn = (wgid % nig) / gsz; return true;
.LBB0_99:
	s_ashr_i32 s5, s5, 3
	s_add_i32 s5, s29, s5
	s_ashr_i32 s26, s5, 31
	s_lshr_b32 s26, s26, 23
	s_add_i32 s26, s5, s26
	s_ashr_i32 s27, s26, 9
	s_lshl_b32 s27, s27, 3
	s_sub_i32 s28, 32, s27
	s_min_i32 s28, s28, 8
	s_abs_i32 s29, s28
	v_cvt_f32_u32_e32 v0, s29
	s_sub_i32 s43, 0, s29
	s_and_b32 s26, s26, 0xfffffe00
	s_sub_i32 s5, s5, s26
	v_rcp_iflag_f32_e32 v0, v0
	s_abs_i32 s26, s5
	s_xor_b32 s42, s5, s28
	s_ashr_i32 s42, s42, 31
	v_mul_f32_e32 v0, 0x4f7ffffe, v0
	v_cvt_u32_f32_e32 v0, v0
	s_nop 0
	v_readfirstlane_b32 s44, v0
	s_mul_i32 s43, s43, s44
	s_mul_hi_u32 s43, s44, s43
	s_add_i32 s44, s44, s43
	s_mul_hi_u32 s43, s26, s44
	s_mul_i32 s44, s43, s29
	s_sub_i32 s26, s26, s44
	s_add_i32 s45, s43, 1
	s_sub_i32 s44, s26, s29
	s_cmp_ge_u32 s26, s29
	s_cselect_b32 s43, s45, s43
	s_cselect_b32 s26, s44, s26
	s_add_i32 s44, s43, 1
	s_cmp_ge_u32 s26, s29
	s_cselect_b32 s26, s44, s43
	s_xor_b32 s26, s26, s42
	s_sub_i32 s26, s26, s42
	s_mul_i32 s28, s26, s28
	s_sub_i32 s5, s5, s28
	s_add_i32 s28, s27, s5
	s_add_i32 s98, s26, s62
	s_and_b32 s98, s98, 3
	s_and_b32 s26, s26, -4
	s_or_b32 s26, s26, s98
